# final RMSNorm loop unrolled 4x with loads issued together, on top of v47
# speedup vs baseline: 1.0029x; 1.0029x over previous
.LBB0_1965:
	s_or_b64 exec, exec, s[6:7]
	v_readlane_b32 s4, v232, 7
	s_waitcnt lgkmcnt(0)
	s_barrier
	v_readlane_b32 s5, v232, 8
	v_ashrrev_i32_e32 v137, 31, v136
	s_nop 0
	v_lshl_add_u64 v[0:1], s[4:5], 0, v[136:137]
	s_mov_b64 s[4:5], 0x800000
	v_cmp_gt_u64_e32 vcc, s[4:5], v[0:1]
	s_and_saveexec_b64 s[4:5], vcc
	s_cbranch_execz .LBB0_1968
	s_load_dwordx2 s[0:1], s[0:1], 0xa8
	s_lshl_b64 s[4:5], s[2:3], 13
	s_add_u32 s4, s28, s4
	v_readlane_b32 s6, v232, 9
	s_addc_u32 s5, s29, s5
	v_readlane_b32 s7, v232, 10
	s_lshl_b64 s[2:3], s[2:3], 11
	v_lshl_add_u64 v[2:3], v[136:137], 4, s[4:5]
	s_lshl_b64 s[4:5], s[6:7], 13
	v_lshl_add_u64 v[4:5], v[136:137], 2, s[2:3]
	s_lshl_b64 s[2:3], s[6:7], 11
	s_mov_b64 s[6:7], 0
	v_mov_b32_e32 v6, 0x358637bd
	s_mov_b32 s10, 0x800000
	s_mov_b64 s[8:9], 0x7fffff
	s_waitcnt lgkmcnt(0)
	s_cmp_eq_u64 exec, -1
	s_cbranch_scc0 .LBB0_1967
	s_mov_b64 s[66:67], 0x800000
	s_lshl_b64 s[50:51], s[46:47], 1
	s_add_u32 s52, s50, s46
	s_addc_u32 s53, s51, s47
	s_lshl_b64 s[54:55], s[46:47], 2
	s_lshl_b64 s[56:57], s[4:5], 1
	s_add_u32 s58, s56, s4
	s_addc_u32 s59, s57, s5
	s_lshl_b64 s[60:61], s[4:5], 2
	s_lshl_b32 s62, s2, 1
	s_mul_i32 s63, s2, 3
	s_lshl_b64 s[64:65], s[2:3], 2
.Lfin_u4:
	v_readfirstlane_b32 s20, v0
	s_add_u32 s20, s20, s52
	s_add_u32 s20, s20, 63
	s_cmp_gt_u32 s20, 0x7fffff
	s_cbranch_scc1 .Lfin_rem
	v_lshrrev_b64 v[64:65], 7, v[0:1]
	v_and_b32_e32 v64, -4, v64
	v_lshl_add_u64 v[64:65], s[18:19], 0, v[64:65]
	global_load_dword v20, v[64:65], off
	v_mov_b32_e32 v56, v2
	v_mov_b32_e32 v57, v3
	global_load_dwordx4 v[24:27], v[56:57], off
	v_and_b32_e32 v66, 0x7fc, v4
	v_lshlrev_b32_e32 v66, 2, v66
	global_load_dwordx4 v[40:43], v66, s[0:1]
	v_lshl_add_u64 v[66:67], v[0:1], 0, s[46:47]
	v_lshrrev_b64 v[64:65], 7, v[66:67]
	v_and_b32_e32 v64, -4, v64
	v_lshl_add_u64 v[64:65], s[18:19], 0, v[64:65]
	global_load_dword v21, v[64:65], off
	v_lshl_add_u64 v[58:59], v[2:3], 0, s[4:5]
	global_load_dwordx4 v[28:31], v[58:59], off
	v_add_u32_e32 v66, s2, v4
	v_and_b32_e32 v66, 0x7fc, v66
	v_lshlrev_b32_e32 v66, 2, v66
	global_load_dwordx4 v[44:47], v66, s[0:1]
	v_lshl_add_u64 v[66:67], v[0:1], 0, s[50:51]
	v_lshrrev_b64 v[64:65], 7, v[66:67]
	v_and_b32_e32 v64, -4, v64
	v_lshl_add_u64 v[64:65], s[18:19], 0, v[64:65]
	global_load_dword v22, v[64:65], off
	v_lshl_add_u64 v[60:61], v[2:3], 0, s[56:57]
	global_load_dwordx4 v[32:35], v[60:61], off
	v_add_u32_e32 v66, s62, v4
	v_and_b32_e32 v66, 0x7fc, v66
	v_lshlrev_b32_e32 v66, 2, v66
	global_load_dwordx4 v[48:51], v66, s[0:1]
	v_lshl_add_u64 v[66:67], v[0:1], 0, s[52:53]
	v_lshrrev_b64 v[64:65], 7, v[66:67]
	v_and_b32_e32 v64, -4, v64
	v_lshl_add_u64 v[64:65], s[18:19], 0, v[64:65]
	global_load_dword v23, v[64:65], off
	v_lshl_add_u64 v[62:63], v[2:3], 0, s[58:59]
	global_load_dwordx4 v[36:39], v[62:63], off
	v_add_u32_e32 v66, s63, v4
	v_and_b32_e32 v66, 0x7fc, v66
	v_lshlrev_b32_e32 v66, 2, v66
	global_load_dwordx4 v[52:55], v66, s[0:1]
	s_waitcnt vmcnt(9)
	v_fmamk_f32 v20, v20, 0x3a000000, v6
	v_mul_f32_e32 v64, 0x4b800000, v20
	v_cmp_gt_f32_e32 vcc, s10, v20
	s_nop 1
	v_cndmask_b32_e32 v20, v20, v64, vcc
	v_rsq_f32_e32 v20, v20
	s_nop 0
	v_mul_f32_e32 v64, 0x45800000, v20
	v_cndmask_b32_e32 v64, v20, v64, vcc
	v_pk_mul_f32 v[24:25], v[24:25], v[64:65] op_sel_hi:[1,0]
	v_pk_mul_f32 v[26:27], v[26:27], v[64:65] op_sel_hi:[1,0]
	v_pk_mul_f32 v[24:25], v[40:41], v[24:25]
	v_pk_mul_f32 v[26:27], v[42:43], v[26:27]
	global_store_dwordx4 v[56:57], v[24:27], off
	s_waitcnt vmcnt(7)
	v_fmamk_f32 v21, v21, 0x3a000000, v6
	v_mul_f32_e32 v64, 0x4b800000, v21
	v_cmp_gt_f32_e32 vcc, s10, v21
	s_nop 1
	v_cndmask_b32_e32 v21, v21, v64, vcc
	v_rsq_f32_e32 v21, v21
	s_nop 0
	v_mul_f32_e32 v64, 0x45800000, v21
	v_cndmask_b32_e32 v64, v21, v64, vcc
	v_pk_mul_f32 v[28:29], v[28:29], v[64:65] op_sel_hi:[1,0]
	v_pk_mul_f32 v[30:31], v[30:31], v[64:65] op_sel_hi:[1,0]
	v_pk_mul_f32 v[28:29], v[44:45], v[28:29]
	v_pk_mul_f32 v[30:31], v[46:47], v[30:31]
	global_store_dwordx4 v[58:59], v[28:31], off
	s_waitcnt vmcnt(5)
	v_fmamk_f32 v22, v22, 0x3a000000, v6
	v_mul_f32_e32 v64, 0x4b800000, v22
	v_cmp_gt_f32_e32 vcc, s10, v22
	s_nop 1
	v_cndmask_b32_e32 v22, v22, v64, vcc
	v_rsq_f32_e32 v22, v22
	s_nop 0
	v_mul_f32_e32 v64, 0x45800000, v22
	v_cndmask_b32_e32 v64, v22, v64, vcc
	v_pk_mul_f32 v[32:33], v[32:33], v[64:65] op_sel_hi:[1,0]
	v_pk_mul_f32 v[34:35], v[34:35], v[64:65] op_sel_hi:[1,0]
	v_pk_mul_f32 v[32:33], v[48:49], v[32:33]
	v_pk_mul_f32 v[34:35], v[50:51], v[34:35]
	global_store_dwordx4 v[60:61], v[32:35], off
	s_waitcnt vmcnt(3)
	v_fmamk_f32 v23, v23, 0x3a000000, v6
	v_mul_f32_e32 v64, 0x4b800000, v23
	v_cmp_gt_f32_e32 vcc, s10, v23
	s_nop 1
	v_cndmask_b32_e32 v23, v23, v64, vcc
	v_rsq_f32_e32 v23, v23
	s_nop 0
	v_mul_f32_e32 v64, 0x45800000, v23
	v_cndmask_b32_e32 v64, v23, v64, vcc
	v_pk_mul_f32 v[36:37], v[36:37], v[64:65] op_sel_hi:[1,0]
	v_pk_mul_f32 v[38:39], v[38:39], v[64:65] op_sel_hi:[1,0]
	v_pk_mul_f32 v[36:37], v[52:53], v[36:37]
	v_pk_mul_f32 v[38:39], v[54:55], v[38:39]
	global_store_dwordx4 v[62:63], v[36:39], off
	v_lshl_add_u64 v[0:1], v[0:1], 0, s[54:55]
	v_lshl_add_u64 v[2:3], v[2:3], 0, s[60:61]
	v_lshl_add_u64 v[4:5], v[4:5], 0, s[64:65]
	s_branch .Lfin_u4
.Lfin_rem:
	v_cmp_gt_u64_e32 vcc, s[66:67], v[0:1]
	s_and_b64 exec, exec, vcc
	s_cbranch_execz .LBB0_1968
